# stack d3: static priority for waves 4-7 (K-loop flips deleted); up-epilogue conv-tap LDS publish moved ahead of the boundary-row stores (no wait on own stores); x->bf16 prologue loop software-pipeline
# speedup vs baseline: 1.0065x; 1.0026x over previous
; __device__ __forceinline__ unsigned pk2(float lo, float hi) { f32x2_t v = {lo, hi}; bf16x2_t b = __builtin_convertvector(v, bf16x2_t); return __builtin_bit_cast(unsigned, b); }
; __device__ __forceinline__ void prologue_phase(const Args& a, LAS unsigned char* lds) {
;     ...
;     float* ss = (float*)(ws + WS_SS); bf16* xb = (bf16*)(ws + WS_XB); const float* x = a.in[I_X];
;     for (int m = gw; m < M; m += NGW) { const f32x4* xr = (const f32x4*)(x + (size_t)m * DM) + lane; unsigned long long* o8 = (unsigned long long*)(xb + (size_t)m * DM) + lane; float s = 0.f;
; #pragma unroll
;         for (int j = 0; j < 8; ++j) { const f32x4 v = xr[64 * j]; s += (v.x * v.x + v.y * v.y) + (v.z * v.z + v.w * v.w); o8[64 * j] = (unsigned long long)pk2(v.x, v.y) | ((unsigned long long)pk2(v.z, v.w) << 32); }
;         s = wave_sum(s); if (lane < 32) ss[(size_t)m * 32 + lane] = (lane == 0) ? s : 0.f; }
.LBB0_87:
	s_cmpk_gt_i32 s26, 0x3fff
	s_cbranch_scc1 .LBB0_92
	v_mbcnt_lo_u32_b32 v4, -1, 0
	v_mbcnt_hi_u32_b32 v4, -1, v4
	v_and_b32_e32 v5, 64, v4
	v_add_u32_e32 v5, 64, v5
	v_xor_b32_e32 v6, 1, v4
	v_cmp_lt_i32_e32 vcc, v6, v5
	s_ashr_i32 s27, s26, 31
	s_lshl_b64 s[0:1], s[26:27], 7
	v_cndmask_b32_e32 v6, v4, v6, vcc
	v_lshlrev_b32_e32 v10, 2, v6
	v_xor_b32_e32 v6, 2, v4
	v_cmp_lt_i32_e32 vcc, v6, v5
	v_mov_b32_e32 v7, 0
	s_ashr_i32 s25, s24, 31
	v_cndmask_b32_e32 v6, v4, v6, vcc
	v_lshlrev_b32_e32 v11, 2, v6
	v_xor_b32_e32 v6, 4, v4
	v_cmp_lt_i32_e32 vcc, v6, v5
	s_lshl_b64 s[14:15], s[24:25], 7
	v_cmp_gt_u32_e64 s[4:5], 32, v3
	v_cndmask_b32_e32 v6, v4, v6, vcc
	v_lshlrev_b32_e32 v12, 2, v6
	v_xor_b32_e32 v6, 8, v4
	v_cmp_lt_i32_e32 vcc, v6, v5
	v_cmp_eq_u32_e64 s[6:7], 0, v3
	s_nop 0
	v_cndmask_b32_e32 v6, v4, v6, vcc
	v_lshlrev_b32_e32 v13, 2, v6
	v_xor_b32_e32 v6, 16, v4
	v_cmp_lt_i32_e32 vcc, v6, v5
	s_nop 1
	v_cndmask_b32_e32 v6, v4, v6, vcc
	v_lshlrev_b32_e32 v14, 2, v6
	v_xor_b32_e32 v6, 32, v4
	v_cmp_lt_i32_e32 vcc, v6, v5
	s_nop 1
	v_cndmask_b32_e32 v4, v4, v6, vcc
	v_lshlrev_b32_e32 v6, 2, v3
	v_lshlrev_b32_e32 v15, 2, v4
	v_lshl_add_u64 v[4:5], s[0:1], 0, v[6:7]
	s_lshl_b64 s[0:1], s[26:27], 13
	s_add_u32 s0, s12, s0
	v_lshlrev_b32_e32 v6, 4, v3
	s_addc_u32 s1, s13, s1
	v_lshl_add_u64 v[6:7], s[0:1], 0, v[6:7]
	s_mov_b64 s[0:1], 0x1000
	v_lshl_add_u64 v[6:7], v[6:7], 0, s[0:1]
	s_lshl_b64 s[0:1], s[26:27], 12
	s_lshl_b64 s[12:13], s[24:25], 13
	v_lshl_or_b32 v8, v3, 3, s0
	v_mov_b32_e32 v9, s1
	s_lshl_b64 s[16:17], s[24:25], 12
	s_mov_b32 s0, 0x14400000
	s_branch .LBB0_90
.LBB0_90:
	s_waitcnt lgkmcnt(0)
	global_load_dwordx4 v[16:19], v[6:7], off offset:-4096
	global_load_dwordx4 v[20:23], v[6:7], off offset:-3072
	global_load_dwordx4 v[24:27], v[6:7], off offset:-2048
	global_load_dwordx4 v[28:31], v[6:7], off offset:-1024
	global_load_dwordx4 v[32:35], v[6:7], off
	global_load_dwordx4 v[36:39], v[6:7], off offset:1024
	global_load_dwordx4 v[40:43], v[6:7], off offset:2048
	global_load_dwordx4 v[44:47], v[6:7], off offset:3072
.Lxc_top:
	s_add_i32 s40, s26, s24
	s_cmpk_gt_i32 s40, 0x3fff
	s_cbranch_scc1 .Lxc_lastA
	v_lshl_add_u64 v[6:7], v[6:7], 0, s[12:13]
	global_load_dwordx4 v[146:149], v[6:7], off offset:-4096
	global_load_dwordx4 v[150:153], v[6:7], off offset:-3072
	global_load_dwordx4 v[154:157], v[6:7], off offset:-2048
	global_load_dwordx4 v[158:161], v[6:7], off offset:-1024
	global_load_dwordx4 v[162:165], v[6:7], off
	global_load_dwordx4 v[166:169], v[6:7], off offset:1024
	global_load_dwordx4 v[170:173], v[6:7], off offset:2048
	global_load_dwordx4 v[174:177], v[6:7], off offset:3072
	v_lshl_add_u64 v[126:127], s[36:37], 0, v[8:9]
	v_add_co_u32_e32 v48, vcc, s0, v126
	s_nop 1
	v_addc_co_u32_e32 v49, vcc, 0, v127, vcc
	s_waitcnt vmcnt(15)
	v_cvt_pk_bf16_f32 v128, v16, v17
	v_cvt_pk_bf16_f32 v129, v18, v19
	global_store_dwordx2 v[48:49], v[128:129], off
	v_mul_f32_e32 v3, v17, v17
	v_mul_f32_e32 v144, v19, v19
	v_fmac_f32_e32 v3, v16, v16
	v_fmac_f32_e32 v144, v18, v18
	v_add_f32_e32 v3, v3, v144
	s_waitcnt vmcnt(15)
	v_cvt_pk_bf16_f32 v130, v20, v21
	v_cvt_pk_bf16_f32 v131, v22, v23
	global_store_dwordx2 v[48:49], v[130:131], off offset:512
	v_mul_f32_e32 v144, v21, v21
	v_mul_f32_e32 v145, v23, v23
	v_fmac_f32_e32 v144, v20, v20
	v_fmac_f32_e32 v145, v22, v22
	v_add_f32_e32 v144, v144, v145
	v_add_f32_e32 v3, v3, v144
	s_waitcnt vmcnt(15)
	v_cvt_pk_bf16_f32 v132, v24, v25
	v_cvt_pk_bf16_f32 v133, v26, v27
	global_store_dwordx2 v[48:49], v[132:133], off offset:1024
	v_mul_f32_e32 v144, v25, v25
	v_mul_f32_e32 v145, v27, v27
	v_fmac_f32_e32 v144, v24, v24
	v_fmac_f32_e32 v145, v26, v26
	v_add_f32_e32 v144, v144, v145
	v_add_f32_e32 v3, v3, v144
	s_waitcnt vmcnt(15)
	v_cvt_pk_bf16_f32 v134, v28, v29
	v_cvt_pk_bf16_f32 v135, v30, v31
	global_store_dwordx2 v[48:49], v[134:135], off offset:1536
	v_mul_f32_e32 v144, v29, v29
	v_mul_f32_e32 v145, v31, v31
	v_fmac_f32_e32 v144, v28, v28
	v_fmac_f32_e32 v145, v30, v30
	v_add_f32_e32 v144, v144, v145
	v_add_f32_e32 v3, v3, v144
	s_waitcnt vmcnt(15)
	v_cvt_pk_bf16_f32 v136, v32, v33
	v_cvt_pk_bf16_f32 v137, v34, v35
	global_store_dwordx2 v[48:49], v[136:137], off offset:2048
	v_mul_f32_e32 v144, v33, v33
	v_mul_f32_e32 v145, v35, v35
	v_fmac_f32_e32 v144, v32, v32
	v_fmac_f32_e32 v145, v34, v34
	v_add_f32_e32 v144, v144, v145
	v_add_f32_e32 v3, v3, v144
	s_waitcnt vmcnt(15)
	v_cvt_pk_bf16_f32 v138, v36, v37
	v_cvt_pk_bf16_f32 v139, v38, v39
	global_store_dwordx2 v[48:49], v[138:139], off offset:2560
	v_mul_f32_e32 v144, v37, v37
	v_mul_f32_e32 v145, v39, v39
	v_fmac_f32_e32 v144, v36, v36
	v_fmac_f32_e32 v145, v38, v38
	v_add_f32_e32 v144, v144, v145
	v_add_f32_e32 v3, v3, v144
	s_waitcnt vmcnt(15)
	v_cvt_pk_bf16_f32 v140, v40, v41
	v_cvt_pk_bf16_f32 v141, v42, v43
	global_store_dwordx2 v[48:49], v[140:141], off offset:3072
	v_mul_f32_e32 v144, v41, v41
	v_mul_f32_e32 v145, v43, v43
	v_fmac_f32_e32 v144, v40, v40
	v_fmac_f32_e32 v145, v42, v42
	v_add_f32_e32 v144, v144, v145
	v_add_f32_e32 v3, v3, v144
	s_waitcnt vmcnt(15)
	v_cvt_pk_bf16_f32 v142, v44, v45
	v_cvt_pk_bf16_f32 v143, v46, v47
	global_store_dwordx2 v[48:49], v[142:143], off offset:3584
	v_mul_f32_e32 v144, v45, v45
	v_mul_f32_e32 v145, v47, v47
	v_fmac_f32_e32 v144, v44, v44
	v_fmac_f32_e32 v145, v46, v46
	v_add_f32_e32 v144, v144, v145
	v_add_f32_e32 v3, v3, v144
	ds_bpermute_b32 v178, v10, v3
	s_waitcnt lgkmcnt(0)
	v_add_f32_e32 v3, v3, v178
	ds_bpermute_b32 v178, v11, v3
	s_waitcnt lgkmcnt(0)
	v_add_f32_e32 v3, v3, v178
	ds_bpermute_b32 v178, v12, v3
	s_waitcnt lgkmcnt(0)
	v_add_f32_e32 v3, v3, v178
	ds_bpermute_b32 v178, v13, v3
	s_waitcnt lgkmcnt(0)
	v_add_f32_e32 v3, v3, v178
	ds_bpermute_b32 v178, v14, v3
	s_waitcnt lgkmcnt(0)
	v_add_f32_e32 v3, v3, v178
	ds_bpermute_b32 v178, v15, v3
	s_and_saveexec_b64 s[2:3], s[4:5]
	s_cbranch_execz .Lxc_skipa
	s_waitcnt lgkmcnt(0)
	v_add_f32_e32 v3, v3, v178
	v_cndmask_b32_e64 v3, 0, v3, s[6:7]
	v_lshl_add_u64 v[180:181], s[36:37], 0, v[4:5]
	global_store_dword v[180:181], v3, off
; __device__ __forceinline__ unsigned pk2(float lo, float hi) { f32x2_t v = {lo, hi}; bf16x2_t b = __builtin_convertvector(v, bf16x2_t); return __builtin_bit_cast(unsigned, b); }
; __device__ __forceinline__ void prologue_phase(const Args& a, LAS unsigned char* lds) {
;     ...
;     for (int m = gw; m < M; m += NGW) { const f32x4* xr = (const f32x4*)(x + (size_t)m * DM) + lane; unsigned long long* o8 = (unsigned long long*)(xb + (size_t)m * DM) + lane; float s = 0.f;
; #pragma unroll
;         for (int j = 0; j < 8; ++j) { const f32x4 v = xr[64 * j]; s += (v.x * v.x + v.y * v.y) + (v.z * v.z + v.w * v.w); o8[64 * j] = (unsigned long long)pk2(v.x, v.y) | ((unsigned long long)pk2(v.z, v.w) << 32); }
;         s = wave_sum(s); if (lane < 32) ss[(size_t)m * 32 + lane] = (lane == 0) ? s : 0.f; }
.Lxc_skipa:
	s_or_b64 exec, exec, s[2:3]
	s_add_i32 s26, s26, s24
	v_lshl_add_u64 v[4:5], v[4:5], 0, s[14:15]
	v_lshl_add_u64 v[8:9], v[8:9], 0, s[16:17]
	s_add_i32 s40, s26, s24
	s_cmpk_gt_i32 s40, 0x3fff
	s_cbranch_scc1 .Lxc_lastB
	v_lshl_add_u64 v[6:7], v[6:7], 0, s[12:13]
	global_load_dwordx4 v[16:19], v[6:7], off offset:-4096
	global_load_dwordx4 v[20:23], v[6:7], off offset:-3072
	global_load_dwordx4 v[24:27], v[6:7], off offset:-2048
	global_load_dwordx4 v[28:31], v[6:7], off offset:-1024
	global_load_dwordx4 v[32:35], v[6:7], off
	global_load_dwordx4 v[36:39], v[6:7], off offset:1024
	global_load_dwordx4 v[40:43], v[6:7], off offset:2048
	global_load_dwordx4 v[44:47], v[6:7], off offset:3072
	v_lshl_add_u64 v[126:127], s[36:37], 0, v[8:9]
	v_add_co_u32_e32 v48, vcc, s0, v126
	s_nop 1
	v_addc_co_u32_e32 v49, vcc, 0, v127, vcc
	s_waitcnt vmcnt(15)
	v_cvt_pk_bf16_f32 v128, v146, v147
	v_cvt_pk_bf16_f32 v129, v148, v149
	global_store_dwordx2 v[48:49], v[128:129], off
	v_mul_f32_e32 v3, v147, v147
	v_mul_f32_e32 v144, v149, v149
	v_fmac_f32_e32 v3, v146, v146
	v_fmac_f32_e32 v144, v148, v148
	v_add_f32_e32 v3, v3, v144
	s_waitcnt vmcnt(15)
	v_cvt_pk_bf16_f32 v130, v150, v151
	v_cvt_pk_bf16_f32 v131, v152, v153
	global_store_dwordx2 v[48:49], v[130:131], off offset:512
	v_mul_f32_e32 v144, v151, v151
	v_mul_f32_e32 v145, v153, v153
	v_fmac_f32_e32 v144, v150, v150
	v_fmac_f32_e32 v145, v152, v152
	v_add_f32_e32 v144, v144, v145
	v_add_f32_e32 v3, v3, v144
	s_waitcnt vmcnt(15)
	v_cvt_pk_bf16_f32 v132, v154, v155
	v_cvt_pk_bf16_f32 v133, v156, v157
	global_store_dwordx2 v[48:49], v[132:133], off offset:1024
	v_mul_f32_e32 v144, v155, v155
	v_mul_f32_e32 v145, v157, v157
	v_fmac_f32_e32 v144, v154, v154
	v_fmac_f32_e32 v145, v156, v156
	v_add_f32_e32 v144, v144, v145
	v_add_f32_e32 v3, v3, v144
	s_waitcnt vmcnt(15)
	v_cvt_pk_bf16_f32 v134, v158, v159
	v_cvt_pk_bf16_f32 v135, v160, v161
	global_store_dwordx2 v[48:49], v[134:135], off offset:1536
	v_mul_f32_e32 v144, v159, v159
	v_mul_f32_e32 v145, v161, v161
	v_fmac_f32_e32 v144, v158, v158
	v_fmac_f32_e32 v145, v160, v160
	v_add_f32_e32 v144, v144, v145
	v_add_f32_e32 v3, v3, v144
	s_waitcnt vmcnt(15)
	v_cvt_pk_bf16_f32 v136, v162, v163
	v_cvt_pk_bf16_f32 v137, v164, v165
	global_store_dwordx2 v[48:49], v[136:137], off offset:2048
	v_mul_f32_e32 v144, v163, v163
	v_mul_f32_e32 v145, v165, v165
	v_fmac_f32_e32 v144, v162, v162
	v_fmac_f32_e32 v145, v164, v164
	v_add_f32_e32 v144, v144, v145
	v_add_f32_e32 v3, v3, v144
	s_waitcnt vmcnt(15)
	v_cvt_pk_bf16_f32 v138, v166, v167
	v_cvt_pk_bf16_f32 v139, v168, v169
	global_store_dwordx2 v[48:49], v[138:139], off offset:2560
	v_mul_f32_e32 v144, v167, v167
	v_mul_f32_e32 v145, v169, v169
	v_fmac_f32_e32 v144, v166, v166
	v_fmac_f32_e32 v145, v168, v168
	v_add_f32_e32 v144, v144, v145
	v_add_f32_e32 v3, v3, v144
	s_waitcnt vmcnt(15)
	v_cvt_pk_bf16_f32 v140, v170, v171
	v_cvt_pk_bf16_f32 v141, v172, v173
	global_store_dwordx2 v[48:49], v[140:141], off offset:3072
	v_mul_f32_e32 v144, v171, v171
	v_mul_f32_e32 v145, v173, v173
	v_fmac_f32_e32 v144, v170, v170
	v_fmac_f32_e32 v145, v172, v172
	v_add_f32_e32 v144, v144, v145
	v_add_f32_e32 v3, v3, v144
	s_waitcnt vmcnt(15)
	v_cvt_pk_bf16_f32 v142, v174, v175
	v_cvt_pk_bf16_f32 v143, v176, v177
	global_store_dwordx2 v[48:49], v[142:143], off offset:3584
	v_mul_f32_e32 v144, v175, v175
	v_mul_f32_e32 v145, v177, v177
	v_fmac_f32_e32 v144, v174, v174
	v_fmac_f32_e32 v145, v176, v176
	v_add_f32_e32 v144, v144, v145
	v_add_f32_e32 v3, v3, v144
	ds_bpermute_b32 v178, v10, v3
	s_waitcnt lgkmcnt(0)
	v_add_f32_e32 v3, v3, v178
	ds_bpermute_b32 v178, v11, v3
	s_waitcnt lgkmcnt(0)
	v_add_f32_e32 v3, v3, v178
	ds_bpermute_b32 v178, v12, v3
	s_waitcnt lgkmcnt(0)
	v_add_f32_e32 v3, v3, v178
	ds_bpermute_b32 v178, v13, v3
	s_waitcnt lgkmcnt(0)
	v_add_f32_e32 v3, v3, v178
	ds_bpermute_b32 v178, v14, v3
	s_waitcnt lgkmcnt(0)
	v_add_f32_e32 v3, v3, v178
	ds_bpermute_b32 v178, v15, v3
	s_and_saveexec_b64 s[2:3], s[4:5]
	s_cbranch_execz .Lxc_skipb
	s_waitcnt lgkmcnt(0)
	v_add_f32_e32 v3, v3, v178
	v_cndmask_b32_e64 v3, 0, v3, s[6:7]
	v_lshl_add_u64 v[180:181], s[36:37], 0, v[4:5]
	global_store_dword v[180:181], v3, off
; __device__ __forceinline__ unsigned pk2(float lo, float hi) { f32x2_t v = {lo, hi}; bf16x2_t b = __builtin_convertvector(v, bf16x2_t); return __builtin_bit_cast(unsigned, b); }
; __device__ __forceinline__ void prologue_phase(const Args& a, LAS unsigned char* lds) {
;     ...
;     for (int m = gw; m < M; m += NGW) { const f32x4* xr = (const f32x4*)(x + (size_t)m * DM) + lane; unsigned long long* o8 = (unsigned long long*)(xb + (size_t)m * DM) + lane; float s = 0.f;
; #pragma unroll
;         for (int j = 0; j < 8; ++j) { const f32x4 v = xr[64 * j]; s += (v.x * v.x + v.y * v.y) + (v.z * v.z + v.w * v.w); o8[64 * j] = (unsigned long long)pk2(v.x, v.y) | ((unsigned long long)pk2(v.z, v.w) << 32); }
;         s = wave_sum(s); if (lane < 32) ss[(size_t)m * 32 + lane] = (lane == 0) ? s : 0.f; }
.Lxc_skipb:
	s_or_b64 exec, exec, s[2:3]
	s_add_i32 s26, s26, s24
	v_lshl_add_u64 v[4:5], v[4:5], 0, s[14:15]
	v_lshl_add_u64 v[8:9], v[8:9], 0, s[16:17]
	s_branch .Lxc_top
.Lxc_lastA:
	v_lshl_add_u64 v[126:127], s[36:37], 0, v[8:9]
	v_add_co_u32_e32 v48, vcc, s0, v126
	s_nop 1
	v_addc_co_u32_e32 v49, vcc, 0, v127, vcc
	s_waitcnt vmcnt(7)
	v_cvt_pk_bf16_f32 v128, v16, v17
	v_cvt_pk_bf16_f32 v129, v18, v19
	global_store_dwordx2 v[48:49], v[128:129], off
	v_mul_f32_e32 v3, v17, v17
	v_mul_f32_e32 v144, v19, v19
	v_fmac_f32_e32 v3, v16, v16
	v_fmac_f32_e32 v144, v18, v18
	v_add_f32_e32 v3, v3, v144
	s_waitcnt vmcnt(7)
	v_cvt_pk_bf16_f32 v130, v20, v21
	v_cvt_pk_bf16_f32 v131, v22, v23
	global_store_dwordx2 v[48:49], v[130:131], off offset:512
	v_mul_f32_e32 v144, v21, v21
	v_mul_f32_e32 v145, v23, v23
	v_fmac_f32_e32 v144, v20, v20
	v_fmac_f32_e32 v145, v22, v22
	v_add_f32_e32 v144, v144, v145
	v_add_f32_e32 v3, v3, v144
	s_waitcnt vmcnt(7)
	v_cvt_pk_bf16_f32 v132, v24, v25
	v_cvt_pk_bf16_f32 v133, v26, v27
	global_store_dwordx2 v[48:49], v[132:133], off offset:1024
	v_mul_f32_e32 v144, v25, v25
	v_mul_f32_e32 v145, v27, v27
	v_fmac_f32_e32 v144, v24, v24
	v_fmac_f32_e32 v145, v26, v26
	v_add_f32_e32 v144, v144, v145
	v_add_f32_e32 v3, v3, v144
	s_waitcnt vmcnt(7)
	v_cvt_pk_bf16_f32 v134, v28, v29
	v_cvt_pk_bf16_f32 v135, v30, v31
	global_store_dwordx2 v[48:49], v[134:135], off offset:1536
	v_mul_f32_e32 v144, v29, v29
	v_mul_f32_e32 v145, v31, v31
	v_fmac_f32_e32 v144, v28, v28
	v_fmac_f32_e32 v145, v30, v30
	v_add_f32_e32 v144, v144, v145
	v_add_f32_e32 v3, v3, v144
	s_waitcnt vmcnt(7)
	v_cvt_pk_bf16_f32 v136, v32, v33
	v_cvt_pk_bf16_f32 v137, v34, v35
	global_store_dwordx2 v[48:49], v[136:137], off offset:2048
	v_mul_f32_e32 v144, v33, v33
	v_mul_f32_e32 v145, v35, v35
	v_fmac_f32_e32 v144, v32, v32
	v_fmac_f32_e32 v145, v34, v34
	v_add_f32_e32 v144, v144, v145
	v_add_f32_e32 v3, v3, v144
	s_waitcnt vmcnt(7)
	v_cvt_pk_bf16_f32 v138, v36, v37
	v_cvt_pk_bf16_f32 v139, v38, v39
	global_store_dwordx2 v[48:49], v[138:139], off offset:2560
	v_mul_f32_e32 v144, v37, v37
	v_mul_f32_e32 v145, v39, v39
	v_fmac_f32_e32 v144, v36, v36
	v_fmac_f32_e32 v145, v38, v38
	v_add_f32_e32 v144, v144, v145
	v_add_f32_e32 v3, v3, v144
	s_waitcnt vmcnt(7)
	v_cvt_pk_bf16_f32 v140, v40, v41
	v_cvt_pk_bf16_f32 v141, v42, v43
	global_store_dwordx2 v[48:49], v[140:141], off offset:3072
	v_mul_f32_e32 v144, v41, v41
	v_mul_f32_e32 v145, v43, v43
	v_fmac_f32_e32 v144, v40, v40
	v_fmac_f32_e32 v145, v42, v42
	v_add_f32_e32 v144, v144, v145
	v_add_f32_e32 v3, v3, v144
	s_waitcnt vmcnt(7)
	v_cvt_pk_bf16_f32 v142, v44, v45
	v_cvt_pk_bf16_f32 v143, v46, v47
	global_store_dwordx2 v[48:49], v[142:143], off offset:3584
	v_mul_f32_e32 v144, v45, v45
	v_mul_f32_e32 v145, v47, v47
	v_fmac_f32_e32 v144, v44, v44
	v_fmac_f32_e32 v145, v46, v46
	v_add_f32_e32 v144, v144, v145
	v_add_f32_e32 v3, v3, v144
	ds_bpermute_b32 v178, v10, v3
	s_waitcnt lgkmcnt(0)
	v_add_f32_e32 v3, v3, v178
	ds_bpermute_b32 v178, v11, v3
	s_waitcnt lgkmcnt(0)
	v_add_f32_e32 v3, v3, v178
	ds_bpermute_b32 v178, v12, v3
	s_waitcnt lgkmcnt(0)
	v_add_f32_e32 v3, v3, v178
	ds_bpermute_b32 v178, v13, v3
	s_waitcnt lgkmcnt(0)
	v_add_f32_e32 v3, v3, v178
	ds_bpermute_b32 v178, v14, v3
	s_waitcnt lgkmcnt(0)
	v_add_f32_e32 v3, v3, v178
	ds_bpermute_b32 v178, v15, v3
	s_and_saveexec_b64 s[2:3], s[4:5]
	s_cbranch_execz .Lxc_skipc
	s_waitcnt lgkmcnt(0)
	v_add_f32_e32 v3, v3, v178
	v_cndmask_b32_e64 v3, 0, v3, s[6:7]
	v_lshl_add_u64 v[180:181], s[36:37], 0, v[4:5]
	global_store_dword v[180:181], v3, off

; __device__ __forceinline__ unsigned pk2(float lo, float hi) { f32x2_t v = {lo, hi}; bf16x2_t b = __builtin_convertvector(v, bf16x2_t); return __builtin_bit_cast(unsigned, b); }
; __device__ __forceinline__ void prologue_phase(const Args& a, LAS unsigned char* lds) {
;     ...
;     for (int m = gw; m < M; m += NGW) { const f32x4* xr = (const f32x4*)(x + (size_t)m * DM) + lane; unsigned long long* o8 = (unsigned long long*)(xb + (size_t)m * DM) + lane; float s = 0.f;
; #pragma unroll
;         for (int j = 0; j < 8; ++j) { const f32x4 v = xr[64 * j]; s += (v.x * v.x + v.y * v.y) + (v.z * v.z + v.w * v.w); o8[64 * j] = (unsigned long long)pk2(v.x, v.y) | ((unsigned long long)pk2(v.z, v.w) << 32); }
;         s = wave_sum(s); if (lane < 32) ss[(size_t)m * 32 + lane] = (lane == 0) ? s : 0.f; }
.Lxc_lastB:
	v_lshl_add_u64 v[126:127], s[36:37], 0, v[8:9]
	v_add_co_u32_e32 v48, vcc, s0, v126
	s_nop 1
	v_addc_co_u32_e32 v49, vcc, 0, v127, vcc
	s_waitcnt vmcnt(7)
	v_cvt_pk_bf16_f32 v128, v146, v147
	v_cvt_pk_bf16_f32 v129, v148, v149
	global_store_dwordx2 v[48:49], v[128:129], off
	v_mul_f32_e32 v3, v147, v147
	v_mul_f32_e32 v144, v149, v149
	v_fmac_f32_e32 v3, v146, v146
	v_fmac_f32_e32 v144, v148, v148
	v_add_f32_e32 v3, v3, v144
	s_waitcnt vmcnt(7)
	v_cvt_pk_bf16_f32 v130, v150, v151
	v_cvt_pk_bf16_f32 v131, v152, v153
	global_store_dwordx2 v[48:49], v[130:131], off offset:512
	v_mul_f32_e32 v144, v151, v151
	v_mul_f32_e32 v145, v153, v153
	v_fmac_f32_e32 v144, v150, v150
	v_fmac_f32_e32 v145, v152, v152
	v_add_f32_e32 v144, v144, v145
	v_add_f32_e32 v3, v3, v144
	s_waitcnt vmcnt(7)
	v_cvt_pk_bf16_f32 v132, v154, v155
	v_cvt_pk_bf16_f32 v133, v156, v157
	global_store_dwordx2 v[48:49], v[132:133], off offset:1024
	v_mul_f32_e32 v144, v155, v155
	v_mul_f32_e32 v145, v157, v157
	v_fmac_f32_e32 v144, v154, v154
	v_fmac_f32_e32 v145, v156, v156
	v_add_f32_e32 v144, v144, v145
	v_add_f32_e32 v3, v3, v144
	s_waitcnt vmcnt(7)
	v_cvt_pk_bf16_f32 v134, v158, v159
	v_cvt_pk_bf16_f32 v135, v160, v161
	global_store_dwordx2 v[48:49], v[134:135], off offset:1536
	v_mul_f32_e32 v144, v159, v159
	v_mul_f32_e32 v145, v161, v161
	v_fmac_f32_e32 v144, v158, v158
	v_fmac_f32_e32 v145, v160, v160
	v_add_f32_e32 v144, v144, v145
	v_add_f32_e32 v3, v3, v144
	s_waitcnt vmcnt(7)
	v_cvt_pk_bf16_f32 v136, v162, v163
	v_cvt_pk_bf16_f32 v137, v164, v165
	global_store_dwordx2 v[48:49], v[136:137], off offset:2048
	v_mul_f32_e32 v144, v163, v163
	v_mul_f32_e32 v145, v165, v165
	v_fmac_f32_e32 v144, v162, v162
	v_fmac_f32_e32 v145, v164, v164
	v_add_f32_e32 v144, v144, v145
	v_add_f32_e32 v3, v3, v144
	s_waitcnt vmcnt(7)
	v_cvt_pk_bf16_f32 v138, v166, v167
	v_cvt_pk_bf16_f32 v139, v168, v169
	global_store_dwordx2 v[48:49], v[138:139], off offset:2560
	v_mul_f32_e32 v144, v167, v167
	v_mul_f32_e32 v145, v169, v169
	v_fmac_f32_e32 v144, v166, v166
	v_fmac_f32_e32 v145, v168, v168
	v_add_f32_e32 v144, v144, v145
	v_add_f32_e32 v3, v3, v144
	s_waitcnt vmcnt(7)
	v_cvt_pk_bf16_f32 v140, v170, v171
	v_cvt_pk_bf16_f32 v141, v172, v173
	global_store_dwordx2 v[48:49], v[140:141], off offset:3072
	v_mul_f32_e32 v144, v171, v171
	v_mul_f32_e32 v145, v173, v173
	v_fmac_f32_e32 v144, v170, v170
	v_fmac_f32_e32 v145, v172, v172
	v_add_f32_e32 v144, v144, v145
	v_add_f32_e32 v3, v3, v144
	s_waitcnt vmcnt(7)
	v_cvt_pk_bf16_f32 v142, v174, v175
	v_cvt_pk_bf16_f32 v143, v176, v177
	global_store_dwordx2 v[48:49], v[142:143], off offset:3584
	v_mul_f32_e32 v144, v175, v175
	v_mul_f32_e32 v145, v177, v177
	v_fmac_f32_e32 v144, v174, v174
	v_fmac_f32_e32 v145, v176, v176
	v_add_f32_e32 v144, v144, v145
	v_add_f32_e32 v3, v3, v144
	ds_bpermute_b32 v178, v10, v3
	s_waitcnt lgkmcnt(0)
	v_add_f32_e32 v3, v3, v178
	ds_bpermute_b32 v178, v11, v3
	s_waitcnt lgkmcnt(0)
	v_add_f32_e32 v3, v3, v178
	ds_bpermute_b32 v178, v12, v3
	s_waitcnt lgkmcnt(0)
	v_add_f32_e32 v3, v3, v178
	ds_bpermute_b32 v178, v13, v3
	s_waitcnt lgkmcnt(0)
	v_add_f32_e32 v3, v3, v178
	ds_bpermute_b32 v178, v14, v3
	s_waitcnt lgkmcnt(0)
	v_add_f32_e32 v3, v3, v178
	ds_bpermute_b32 v178, v15, v3
	s_and_saveexec_b64 s[2:3], s[4:5]
	s_cbranch_execz .Lxc_skipd
	s_waitcnt lgkmcnt(0)
	v_add_f32_e32 v3, v3, v178
	v_cndmask_b32_e64 v3, 0, v3, s[6:7]
	v_lshl_add_u64 v[180:181], s[36:37], 0, v[4:5]
	global_store_dword v[180:181], v3, off
.Lxc_skipd:
	s_or_b64 exec, exec, s[2:3]
	s_add_i32 s26, s26, s24
	v_lshl_add_u64 v[4:5], v[4:5], 0, s[14:15]
	v_lshl_add_u64 v[8:9], v[8:9], 0, s[16:17]

; #define PG8_LAS __attribute__((address_space(3)))
;     __device__ __forceinline__ void operator()(f32x4 (&acc)[2][2][4][2], const Unit& u, int wr, int wc, int fr_, int fq_) const {
;     ...
;         const f32x2w wld = *(const f32x2w*)((wk < 3 ? cw + wk * NUP_ : cb) + wgv * DFF_ + u.pn * HALF + wch);
;         const int t0 = (wr * 16 + fr) * 8;
;         { const f32x4 r0 = *(const PG8_LAS f32x4*)(RS + t0), r1 = *(const PG8_LAS f32x4*)(RS + t0 + 4);
; #pragma unroll
;           for (int m = 0; m < 4; ++m)
; #pragma unroll
;             for (int bj = 0; bj < 2; ++bj)
; #pragma unroll
;                 for (int n = 0; n < 2; ++n) { acc[0][bj][m][n] *= r0[m]; acc[1][bj][m][n] *= r1[m]; } }
;         const int colb = wc * 32 + 8 * fq;
;         if (wr == 0 && fr == 15) {
; #pragma unroll
;             for (int bj = 0; bj < 2; ++bj)
; #pragma unroll
;                 for (int n = 0; n < 2; ++n) { *(PG8_LAS f32x4*)(X + bj * HALF + n * 4 + colb) = acc[1][bj][2][n]; *(PG8_LAS f32x4*)(X + 256 + bj * HALF + n * 4 + colb) = acc[1][bj][3][n]; } }
;         { float* hb = hbuf + (size_t)u.pm * 4 * NUP_ + u.pn * BM + colb;
;           if (wr == 0 && fr == 0) {
; #pragma unroll
;               for (int bj = 0; bj < 2; ++bj)
; #pragma unroll
;                   for (int n = 0; n < 2; ++n) { *(f32x4*)(hb + bj * HALF + n * 4) = acc[0][bj][0][n]; *(f32x4*)(hb + (size_t)NUP_ + bj * HALF + n * 4) = acc[0][bj][1][n]; } }
;           if (wr == 1 && fr == 15) {
; #pragma unroll
;               for (int bj = 0; bj < 2; ++bj)
; #pragma unroll
;                   for (int n = 0; n < 2; ++n) { *(f32x4*)(hb + (size_t)2 * NUP_ + bj * HALF + n * 4) = acc[1][bj][2][n]; *(f32x4*)(hb + (size_t)3 * NUP_ + bj * HALF + n * 4) = acc[1][bj][3][n]; } } }
;         *(PG8_LAS f32x2w*)(CW + t2) = wld;
.LBB0_696:
	s_or_b64 exec, exec, s[2:3]
	s_mul_i32 s3, s84, 0x2c000
	s_mul_hi_i32 s2, s84, 0x2c000
	s_add_u32 s4, s46, s3
	s_addc_u32 s5, s47, s2
	s_lshl_b32 s2, s85, 8
	s_ashr_i32 s3, s2, 31
	s_lshl_b64 s[2:3], s[2:3], 2
	s_add_u32 s2, s4, s2
	v_pk_mul_f32 v[136:137], v[92:93], v[164:165] op_sel:[0,1]
	s_addc_u32 s3, s5, s3
	v_ashrrev_i32_e32 v215, 31, v214
	v_or_b32_e32 v92, s34, v169
	v_pk_mul_f32 v[70:71], v[130:131], v[164:165] op_sel_hi:[1,0]
	v_pk_mul_f32 v[72:73], v[132:133], v[164:165] op_sel_hi:[1,0]
	v_pk_mul_f32 v[130:131], v[118:119], v[164:165] op_sel_hi:[1,0]
	v_pk_mul_f32 v[132:133], v[120:121], v[164:165] op_sel_hi:[1,0]
	v_pk_mul_f32 v[66:67], v[102:103], v[164:165] op_sel_hi:[1,0]
	v_pk_mul_f32 v[68:69], v[104:105], v[164:165] op_sel_hi:[1,0]
	v_pk_mul_f32 v[142:143], v[74:75], v[164:165] op_sel_hi:[1,0]
	v_pk_mul_f32 v[144:145], v[76:77], v[164:165] op_sel_hi:[1,0]
	v_pk_mul_f32 v[74:75], v[110:111], v[164:165] op_sel:[0,1]
	v_pk_mul_f32 v[76:77], v[112:113], v[164:165] op_sel:[0,1]
	v_pk_mul_f32 v[138:139], v[98:99], v[164:165] op_sel:[0,1]
	v_pk_mul_f32 v[140:141], v[100:101], v[164:165] op_sel:[0,1]
	v_pk_mul_f32 v[78:79], v[78:79], v[164:165] op_sel:[0,1]
	v_pk_mul_f32 v[80:81], v[80:81], v[164:165] op_sel:[0,1]
	v_pk_mul_f32 v[134:135], v[90:91], v[164:165] op_sel:[0,1]
	v_lshlrev_b32_e32 v216, 1, v170
	v_lshl_add_u32 v216, v216, 2, s72
	s_waitcnt vmcnt(0)
	ds_write_b64 v216, v[162:163]
	v_lshl_add_u64 v[90:91], v[214:215], 2, s[2:3]
	v_cmp_eq_u32_e64 s[4:5], 0, v92
	s_and_saveexec_b64 s[2:3], s[4:5]
	s_cbranch_execz .LBB0_698
	v_add_co_u32_e32 v92, vcc, 0xb000, v90
	global_store_dwordx4 v[90:91], v[70:73], off
	s_nop 0
	v_addc_co_u32_e32 v93, vcc, 0, v91, vcc
	global_store_dwordx4 v[92:93], v[74:77], off
	global_store_dwordx4 v[90:91], v[130:133], off offset:16
	global_store_dwordx4 v[92:93], v[138:141], off offset:16
	global_store_dwordx4 v[90:91], v[66:69], off offset:512
	global_store_dwordx4 v[92:93], v[78:81], off offset:512
	global_store_dwordx4 v[90:91], v[142:145], off offset:528
	global_store_dwordx4 v[92:93], v[134:137], off offset:528

; #define PG8_LAS __attribute__((address_space(3)))
;     __device__ __forceinline__ void operator()(f32x4 (&acc)[2][2][4][2], const Unit& u, int wr, int wc, int fr_, int fq_) const {
;     ...
;         *(PG8_LAS f32x2w*)(CW + t2) = wld;
;         asm volatile("s_waitcnt lgkmcnt(0)" ::: "memory"); __builtin_amdgcn_s_barrier(); asm volatile("" ::: "memory");
;         u32x2 pk[2][8];
;         const bool defer01 = (u.pm & 31) != 0 && wr == 0 && fr == 0;
; #pragma unroll
;         for (int n = 0; n < 2; ++n) { const int chl = wc * 32 + 8 * fq + 4 * n;
;             const f32x4 wg0 = *(const PG8_LAS f32x4*)(CW + chl), wg1 = *(const PG8_LAS f32x4*)(CW + 256 + chl), wg2 = *(const PG8_LAS f32x4*)(CW + 512 + chl), bg = *(const PG8_LAS f32x4*)(CW + 768 + chl);
;             const f32x4 wv0 = *(const PG8_LAS f32x4*)(CW + 128 + chl), wv1 = *(const PG8_LAS f32x4*)(CW + 384 + chl), wv2 = *(const PG8_LAS f32x4*)(CW + 640 + chl), bv = *(const PG8_LAS f32x4*)(CW + 896 + chl);
;             f32x4 h6g = (f32x4){0.f, 0.f, 0.f, 0.f}, h7g = h6g, h6v = h6g, h7v = h6g;
;             if (wr == 1 && fr == 0) { h6g = *(const PG8_LAS f32x4*)(X + n * 4 + colb); h7g = *(const PG8_LAS f32x4*)(X + 256 + n * 4 + colb); h6v = *(const PG8_LAS f32x4*)(X + HALF + n * 4 + colb); h7v = *(const PG8_LAS f32x4*)(X + 256 + HALF + n * 4 + colb); }
.LBB0_700:
	s_or_b64 exec, exec, s[2:3]
	v_lshlrev_b32_e32 v90, 2, v214
	s_add_i32 s2, 0, 0x20000
	v_add_u32_e32 v249, s2, v90
	s_add_i32 s2, 0, 0x20400
	v_add_u32_e32 v94, 0, v90
	s_waitcnt lgkmcnt(0)
	s_barrier
	v_add_u32_e32 v254, s2, v90
	v_add_u32_e32 v232, s73, v90
	v_add_u32_e32 v233, s76, v90
	v_add_u32_e32 v91, s72, v90
	v_add_u32_e32 v90, 0x22900, v94
	ds_read_b128 v[106:109], v91
	ds_read_b128 v[110:113], v90
	v_add_u32_e32 v90, 0x22d00, v94
	v_add_u32_e32 v91, 0x23100, v94
	ds_read_b128 v[114:117], v90
	ds_read_b128 v[118:121], v91
	v_add_u32_e32 v90, 0x22700, v94
	v_add_u32_e32 v95, 0x22b00, v94
	ds_read_b128 v[90:93], v90
	ds_read_b128 v[102:105], v95
	v_add_u32_e32 v95, 0x22f00, v94
	v_add_u32_e32 v98, 0x23300, v94
	ds_read_b128 v[94:97], v95
	ds_read_b128 v[98:101], v98
	v_cmp_eq_u32_e32 vcc, 0, v169
	v_mov_b32_e32 v198, 0
	s_and_b64 s[6:7], s[14:15], vcc
	v_mov_b32_e32 v228, 0
	v_mov_b32_e32 v229, 0
	v_mov_b32_e32 v230, 0
	v_mov_b32_e32 v231, 0
	v_mov_b32_e32 v220, 0
	v_mov_b32_e32 v221, 0
	v_mov_b32_e32 v222, 0
	v_mov_b32_e32 v223, 0
	v_mov_b32_e32 v224, 0
	v_mov_b32_e32 v225, 0
	v_mov_b32_e32 v226, 0
	v_mov_b32_e32 v227, 0
	v_mov_b32_e32 v216, 0
	v_mov_b32_e32 v217, 0
	v_mov_b32_e32 v218, 0
	v_mov_b32_e32 v219, 0
	s_and_saveexec_b64 s[2:3], s[6:7]
	s_cbranch_execz .LBB0_702
	ds_read_b128 v[228:231], v249
	ds_read_b128 v[220:223], v254
	ds_read_b128 v[224:227], v232
	ds_read_b128 v[216:219], v233
